# GEMM phase ramp: all 7 first half-tile LDS-DMA groups issued before the first counted wait (vmcnt 8 then 6), in all 15 GEMM instances
# baseline (speedup 1.0000x reference)
; #define PG8_STAGE(bufoff, gbase, voff) do { _Pragma("unroll") for (int _i = 0; _i < 2; ++_i) \
;         __builtin_amdgcn_global_load_lds((const unsigned*)((const char*)(gbase) + (voff)[_i]), (LAS unsigned*)(lds + (bufoff) + ldsw + _i * 8192), 16, 0, 0); } while (0)
; #define PG8_WAIT_V(n) asm volatile("s_waitcnt vmcnt(" #n ")" ::: "memory")
; #define PG8_BAR __builtin_amdgcn_s_barrier()
; template <class Epi>
; __device__ __forceinline__ void gemm_phase(LAS unsigned char* lds, const Gemm g, const StaticOrder& S, const Epi& E, const int wid) {
;     ...
;     for (int i = 0; i < 2; ++i) { int R, C; stage_rc(tid * 16 + i * 8192, R, C); const int Rb = Epi::PERM ? ((R & ~31) + perm32(R & 31)) : R;
;         voffA[i] = (unsigned)(R * lda + C) * 2u; voffB[i] = (unsigned)(Rb * K + C) * 2u; }
;     const size_t kstep = (size_t)(BK * 2);
;     const size_t hsA = (size_t)HALF * lda * 2, hsB = (size_t)HALF * K * 2;
;     const size_t tsA = 2 * hsA, tsB = 2 * hsB;
;     const unsigned ldsw = (unsigned)wid * 1024u;
;     const int aoff = lds_byte(wr * 64 + fr, fq * 8), boff = lds_byte(wc * 32 + fr, fq * 8);
;     ...
;     PG8_STAGE(PG8_SB(0, 0), cB, voffB); PG8_STAGE(PG8_SB(0, 1), cB + hsB, voffB); PG8_STAGE(PG8_SA(0, 0), cA, voffA); PG8_STAGE(PG8_SA(0, 1), cA + hsA, voffA);
;     if (wr == 1) PG8_BAR;
;     PG8_WAIT_V(2); PG8_BAR;
;     PG8_STAGE(PG8_SB(1, 0), cB + kstep, voffB); PG8_STAGE(PG8_SA(1, 0), cA + kstep, voffA); PG8_STAGE(PG8_SB(1, 1), cB + hsB + kstep, voffB);
;     PG8_WAIT_V(6); PG8_BAR;
.LBB0_181:
	s_add_u32 s8, s54, 0x500000
	s_addc_u32 s9, s55, 0
	s_add_u32 s10, s54, 0x700000
	s_mov_b64 s[14:15], 0x80
	s_addc_u32 s11, s55, 0
	s_add_i32 m0, s66, 0x18000
	v_lshl_add_u64 v[6:7], v[6:7], 0, s[14:15]
	global_load_lds_dwordx4 v[6:7], off
	v_lshl_add_u64 v[4:5], v[4:5], 0, s[14:15]
	s_add_i32 m0, s66, 0x1a000
	s_add_i32 s76, s66, 0x8000
	s_add_i32 s77, s66, 0xa000
	global_load_lds_dwordx4 v[4:5], off
	v_lshl_add_u64 v[0:1], v[0:1], 0, s[14:15]
	s_mov_b32 m0, s76
	s_add_u32 s16, s34, 0x40080
	global_load_lds_dwordx4 v[0:1], off
	v_lshl_add_u64 v[0:1], v[2:3], 0, s[14:15]
	s_mov_b32 m0, s77
	s_addc_u32 s17, s35, 0
	global_load_lds_dwordx4 v[0:1], off
	s_add_i32 m0, s66, 0x1c000
	v_lshl_add_u64 v[0:1], s[16:17], 0, v[138:139]
	global_load_lds_dwordx4 v[0:1], off
	v_lshl_add_u64 v[0:1], s[16:17], 0, v[142:143]
	s_add_i32 m0, s66, 0x1e000
	s_sext_i32_i8 s93, s0
	global_load_lds_dwordx4 v[0:1], off
	s_waitcnt vmcnt(8)
	s_barrier
	v_and_b32_e32 v0, 15, v8
	v_ashrrev_i32_e32 v1, 6, v8
	v_and_b32_e32 v2, 48, v8
	v_readlane_b32 s0, v254, 3
	v_lshl_or_b32 v0, v0, 6, v2
	v_lshlrev_b32_e32 v3, 2, v8
	v_lshl_add_u32 v2, v1, 10, s0
	v_readlane_b32 s0, v254, 5
	v_and_b32_e32 v3, 32, v3
	v_bitop3_b32 v2, v0, v2, v3 bitop3:0xde
	v_add_lshl_u32 v1, v1, s0, 10
	v_bitop3_b32 v170, v0, v1, v3 bitop3:0xde
	v_lshlrev_b32_e32 v0, 14, v12
	v_and_b32_e32 v0, 0xffff8000, v0
	v_lshl_add_u32 v0, v13, 11, v0
	v_and_b32_e32 v1, 1, v12
	v_lshl_or_b32 v0, v1, 6, v0
	v_lshl_add_u32 v146, v14, 1, v0
	v_lshlrev_b32_e32 v0, 14, v9
	v_and_b32_e32 v0, 0xffff8000, v0
	s_waitcnt vmcnt(6)
	s_cmpk_lt_u32 s3, 0x100
	v_lshl_add_u32 v0, v10, 11, v0
	v_and_b32_e32 v1, 1, v9
	s_cselect_b64 s[16:17], -1, 0
	s_lshl_b32 s0, s33, 4
	v_lshl_or_b32 v0, v1, 6, v0
	s_add_i32 s81, 0, 0x10000
	s_add_i32 s82, 0, 0x14000
	s_and_b32 s78, s0, 0x3fffffc0
	s_ashr_i32 s79, s56, 31
	s_mov_b32 s80, s56
	v_mov_b32_e32 v147, v145
	v_lshl_add_u32 v148, v11, 1, v0
	v_mov_b32_e32 v149, v145
	v_mov_b64_e32 v[150:151], 0x800
	v_mov_b64_e32 v[152:153], 0x7ff
	v_add_u32_e32 v171, s81, v170
	v_add_u32_e32 v172, s82, v170
	v_add_u32_e32 v173, 0, v2
	v_mov_b32_e32 v174, 0x358637bd
	s_mov_b64 s[18:19], 0x90000
	s_mov_b32 s83, 0x90000
	s_mov_b64 s[20:21], 0xa0000
	s_mov_b32 s90, 0xa0000
	s_mov_b64 s[22:23], 0xb0000
	s_mov_b32 s91, 0xb0000
	v_mov_b32_e32 v175, 0x3d800000
	v_mov_b32_e32 v176, 0x4000
	s_mov_b32 s92, 0
	s_barrier
	s_branch .LBB0_184

; #define PG8_STAGE(bufoff, gbase, voff) do { _Pragma("unroll") for (int _i = 0; _i < 2; ++_i) \
;         __builtin_amdgcn_global_load_lds((const unsigned*)((const char*)(gbase) + (voff)[_i]), (LAS unsigned*)(lds + (bufoff) + ldsw + _i * 8192), 16, 0, 0); } while (0)
; #define PG8_WAIT_V(n) asm volatile("s_waitcnt vmcnt(" #n ")" ::: "memory")
; #define PG8_BAR __builtin_amdgcn_s_barrier()
; template <class Epi>
; __device__ __forceinline__ void gemm_phase(LAS unsigned char* lds, const Gemm g, const StaticOrder& S, const Epi& E, const int wid) {
;     ...
;     for (int i = 0; i < 2; ++i) { int R, C; stage_rc(tid * 16 + i * 8192, R, C); const int Rb = Epi::PERM ? ((R & ~31) + perm32(R & 31)) : R;
;         voffA[i] = (unsigned)(R * lda + C) * 2u; voffB[i] = (unsigned)(Rb * K + C) * 2u; }
;     const size_t kstep = (size_t)(BK * 2);
;     const size_t hsA = (size_t)HALF * lda * 2, hsB = (size_t)HALF * K * 2;
;     const size_t tsA = 2 * hsA, tsB = 2 * hsB;
;     const unsigned ldsw = (unsigned)wid * 1024u;
;     const int aoff = lds_byte(wr * 64 + fr, fq * 8), boff = lds_byte(wc * 32 + fr, fq * 8);
;     ...
;     PG8_STAGE(PG8_SB(0, 0), cB, voffB); PG8_STAGE(PG8_SB(0, 1), cB + hsB, voffB); PG8_STAGE(PG8_SA(0, 0), cA, voffA); PG8_STAGE(PG8_SA(0, 1), cA + hsA, voffA);
;     if (wr == 1) PG8_BAR;
;     PG8_WAIT_V(2); PG8_BAR;
;     PG8_STAGE(PG8_SB(1, 0), cB + kstep, voffB); PG8_STAGE(PG8_SA(1, 0), cA + kstep, voffA); PG8_STAGE(PG8_SB(1, 1), cB + hsB + kstep, voffB);
;     PG8_WAIT_V(6); PG8_BAR;
.LBB0_321:
	s_mov_b64 s[6:7], 0x80
	s_add_i32 m0, s23, 0x18000
	v_lshl_add_u64 v[6:7], v[6:7], 0, s[6:7]
	global_load_lds_dwordx4 v[6:7], off
	v_lshl_add_u64 v[4:5], v[4:5], 0, s[6:7]
	s_add_i32 m0, s23, 0x1a000
	s_add_i32 s64, s23, 0x8000
	s_add_i32 s65, s23, 0xa000
	global_load_lds_dwordx4 v[4:5], off
	v_lshl_add_u64 v[0:1], v[0:1], 0, s[6:7]
	s_mov_b32 m0, s64
	s_add_u32 s0, s24, 0x40080
	global_load_lds_dwordx4 v[0:1], off
	v_lshl_add_u64 v[0:1], v[2:3], 0, s[6:7]
	s_mov_b32 m0, s65
	s_addc_u32 s1, s25, 0
	global_load_lds_dwordx4 v[0:1], off
	s_add_i32 m0, s23, 0x1c000
	v_lshl_add_u64 v[0:1], s[0:1], 0, v[170:171]
	global_load_lds_dwordx4 v[0:1], off
	v_lshl_add_u64 v[0:1], s[0:1], 0, v[174:175]
	s_add_i32 m0, s23, 0x1e000
	v_and_b32_e32 v2, 48, v8
	global_load_lds_dwordx4 v[0:1], off
	s_waitcnt vmcnt(8)
	s_barrier
	v_and_b32_e32 v0, 15, v8
	v_ashrrev_i32_e32 v1, 6, v8
	v_readlane_b32 s0, v254, 3
	v_lshl_or_b32 v0, v0, 6, v2
	v_lshlrev_b32_e32 v3, 2, v8
	v_lshl_add_u32 v2, v1, 10, s0
	v_readlane_b32 s0, v254, 5
	v_and_b32_e32 v3, 32, v3
	v_bitop3_b32 v2, v0, v2, v3 bitop3:0xde
	v_add_lshl_u32 v1, v1, s0, 10
	v_bitop3_b32 v194, v0, v1, v3 bitop3:0xde
	v_lshlrev_b32_e32 v0, 14, v12
	v_and_b32_e32 v0, 0xffff8000, v0
	v_lshl_add_u32 v0, v13, 11, v0
	v_and_b32_e32 v1, 1, v12
	v_lshl_or_b32 v0, v1, 6, v0
	v_lshl_add_u32 v176, v14, 1, v0
	v_lshlrev_b32_e32 v0, 14, v9
	v_and_b32_e32 v0, 0xffff8000, v0
	s_waitcnt vmcnt(6)
	s_cmpk_lt_u32 s3, 0x100
	v_lshl_add_u32 v0, v10, 11, v0
	v_and_b32_e32 v1, 1, v9
	s_cselect_b64 s[8:9], -1, 0
	s_lshl_b32 s0, s33, 4
	v_lshl_or_b32 v0, v1, 6, v0
	s_add_i32 s76, 0, 0x10000
	s_add_i32 s77, 0, 0x14000
	s_and_b32 s66, s0, 0x3fffffc0
	s_ashr_i32 s67, s56, 31
	s_mov_b32 s74, s56
	s_ashr_i32 s75, s2, 31
	v_mov_b32_e32 v177, v171
	v_lshl_add_u32 v178, v11, 1, v0
	v_mov_b32_e32 v179, v171
	v_mov_b64_e32 v[180:181], 0x400
	v_mov_b64_e32 v[182:183], 0x3ff
	v_add_u32_e32 v195, s76, v194
	v_add_u32_e32 v196, s77, v194
	v_add_u32_e32 v197, 0, v2
	v_mov_b32_e32 v198, 0x358637bd
	s_barrier
	s_branch .LBB0_324

; #define PG8_STAGE(bufoff, gbase, voff) do { _Pragma("unroll") for (int _i = 0; _i < 2; ++_i) \
;         __builtin_amdgcn_global_load_lds((const unsigned*)((const char*)(gbase) + (voff)[_i]), (LAS unsigned*)(lds + (bufoff) + ldsw + _i * 8192), 16, 0, 0); } while (0)
; #define PG8_WAIT_V(n) asm volatile("s_waitcnt vmcnt(" #n ")" ::: "memory")
; #define PG8_BAR __builtin_amdgcn_s_barrier()
; template <class Epi>
; __device__ __forceinline__ void gemm_phase(LAS unsigned char* lds, const Gemm g, const StaticOrder& S, const Epi& E, const int wid) {
;     ...
;     for (int i = 0; i < 2; ++i) { int R, C; stage_rc(tid * 16 + i * 8192, R, C); const int Rb = Epi::PERM ? ((R & ~31) + perm32(R & 31)) : R;
;         voffA[i] = (unsigned)(R * lda + C) * 2u; voffB[i] = (unsigned)(Rb * K + C) * 2u; }
;     const size_t kstep = (size_t)(BK * 2);
;     const size_t hsA = (size_t)HALF * lda * 2, hsB = (size_t)HALF * K * 2;
;     const size_t tsA = 2 * hsA, tsB = 2 * hsB;
;     const unsigned ldsw = (unsigned)wid * 1024u;
;     const int aoff = lds_byte(wr * 64 + fr, fq * 8), boff = lds_byte(wc * 32 + fr, fq * 8);
;     ...
;     PG8_STAGE(PG8_SB(0, 0), cB, voffB); PG8_STAGE(PG8_SB(0, 1), cB + hsB, voffB); PG8_STAGE(PG8_SA(0, 0), cA, voffA); PG8_STAGE(PG8_SA(0, 1), cA + hsA, voffA);
;     if (wr == 1) PG8_BAR;
;     PG8_WAIT_V(2); PG8_BAR;
;     PG8_STAGE(PG8_SB(1, 0), cB + kstep, voffB); PG8_STAGE(PG8_SA(1, 0), cA + kstep, voffA); PG8_STAGE(PG8_SB(1, 1), cB + hsB + kstep, voffB);
;     PG8_WAIT_V(6); PG8_BAR;
.LBB0_391:
	s_mov_b64 s[8:9], 0x80
	s_add_i32 m0, s25, 0x18000
	v_lshl_add_u64 v[6:7], v[6:7], 0, s[8:9]
	global_load_lds_dwordx4 v[6:7], off
	v_lshl_add_u64 v[4:5], v[4:5], 0, s[8:9]
	s_add_i32 m0, s25, 0x1a000
	s_add_i32 s64, s25, 0x8000
	s_add_i32 s65, s25, 0xa000
	global_load_lds_dwordx4 v[4:5], off
	v_lshl_add_u64 v[0:1], v[0:1], 0, s[8:9]
	s_mov_b32 m0, s64
	s_add_u32 s4, s26, 0x80080
	global_load_lds_dwordx4 v[0:1], off
	v_lshl_add_u64 v[0:1], v[2:3], 0, s[8:9]
	s_mov_b32 m0, s65
	s_addc_u32 s5, s27, 0
	global_load_lds_dwordx4 v[0:1], off
	s_add_i32 m0, s25, 0x1c000
	v_lshl_add_u64 v[0:1], s[4:5], 0, v[194:195]
	global_load_lds_dwordx4 v[0:1], off
	v_lshl_add_u64 v[0:1], s[4:5], 0, v[198:199]
	s_add_i32 m0, s25, 0x1e000
	v_and_b32_e32 v2, 48, v8
	global_load_lds_dwordx4 v[0:1], off
	s_waitcnt vmcnt(8)
	s_barrier
	v_and_b32_e32 v0, 15, v8
	v_ashrrev_i32_e32 v1, 6, v8
	v_readlane_b32 s1, v254, 3
	v_lshl_or_b32 v0, v0, 6, v2
	v_lshlrev_b32_e32 v3, 2, v8
	v_lshl_add_u32 v2, v1, 10, s1
	v_readlane_b32 s1, v254, 5
	v_and_b32_e32 v3, 32, v3
	v_bitop3_b32 v2, v0, v2, v3 bitop3:0xde
	v_add_lshl_u32 v1, v1, s1, 10
	v_bitop3_b32 v245, v0, v1, v3 bitop3:0xde
	v_lshlrev_b32_e32 v0, 15, v12
	v_and_b32_e32 v0, 0xffff0000, v0
	v_lshl_add_u32 v0, v13, 12, v0
	v_and_b32_e32 v1, 1, v12
	v_lshl_or_b32 v0, v1, 6, v0
	v_lshl_add_u32 v200, v14, 1, v0
	v_lshlrev_b32_e32 v0, 15, v9
	v_and_b32_e32 v0, 0xffff0000, v0
	s_waitcnt vmcnt(6)
	s_cmpk_lt_u32 s3, 0x100
	v_lshl_add_u32 v0, v10, 12, v0
	v_and_b32_e32 v1, 1, v9
	s_cselect_b64 s[10:11], -1, 0
	s_lshl_b32 s1, s33, 4
	v_lshl_or_b32 v0, v1, 6, v0
	s_add_i32 s76, 0, 0x10000
	s_add_i32 s77, 0, 0x14000
	s_and_b32 s66, s1, 0x3fffffc0
	s_ashr_i32 s67, s56, 31
	s_mov_b32 s74, s56
	s_ashr_i32 s75, s2, 31
	v_mov_b32_e32 v201, v195
	v_lshl_add_u32 v202, v11, 1, v0
	v_mov_b32_e32 v203, v195
	v_mov_b64_e32 v[204:205], 0x200
	v_mov_b64_e32 v[206:207], 0x1ff
	v_add_u32_e32 v246, s76, v245
	v_add_u32_e32 v247, s77, v245
	v_add_u32_e32 v248, 0, v2
	v_mbcnt_hi_u32_b32 v249, -1, v244
	s_barrier
	s_branch .LBB0_394

; #define PG8_STAGE(bufoff, gbase, voff) do { _Pragma("unroll") for (int _i = 0; _i < 2; ++_i) \
;         __builtin_amdgcn_global_load_lds((const unsigned*)((const char*)(gbase) + (voff)[_i]), (LAS unsigned*)(lds + (bufoff) + ldsw + _i * 8192), 16, 0, 0); } while (0)
; #define PG8_WAIT_V(n) asm volatile("s_waitcnt vmcnt(" #n ")" ::: "memory")
; #define PG8_BAR __builtin_amdgcn_s_barrier()
; template <class Epi>
; __device__ __forceinline__ void gemm_phase(LAS unsigned char* lds, const Gemm g, const StaticOrder& S, const Epi& E, const int wid) {
;     ...
;     for (int i = 0; i < 2; ++i) { int R, C; stage_rc(tid * 16 + i * 8192, R, C); const int Rb = Epi::PERM ? ((R & ~31) + perm32(R & 31)) : R;
;         voffA[i] = (unsigned)(R * lda + C) * 2u; voffB[i] = (unsigned)(Rb * K + C) * 2u; }
;     const size_t kstep = (size_t)(BK * 2);
;     const size_t hsA = (size_t)HALF * lda * 2, hsB = (size_t)HALF * K * 2;
;     const size_t tsA = 2 * hsA, tsB = 2 * hsB;
;     const unsigned ldsw = (unsigned)wid * 1024u;
;     const int aoff = lds_byte(wr * 64 + fr, fq * 8), boff = lds_byte(wc * 32 + fr, fq * 8);
;     ...
;     PG8_STAGE(PG8_SB(0, 0), cB, voffB); PG8_STAGE(PG8_SB(0, 1), cB + hsB, voffB); PG8_STAGE(PG8_SA(0, 0), cA, voffA); PG8_STAGE(PG8_SA(0, 1), cA + hsA, voffA);
;     if (wr == 1) PG8_BAR;
;     PG8_WAIT_V(2); PG8_BAR;
;     PG8_STAGE(PG8_SB(1, 0), cB + kstep, voffB); PG8_STAGE(PG8_SA(1, 0), cA + kstep, voffA); PG8_STAGE(PG8_SB(1, 1), cB + hsB + kstep, voffB);
;     PG8_WAIT_V(6); PG8_BAR;
.LBB0_475:
	s_mov_b64 s[8:9], 0x80
	s_add_i32 m0, s35, 0x18000
	v_lshl_add_u64 v[6:7], v[6:7], 0, s[8:9]
	global_load_lds_dwordx4 v[6:7], off
	v_lshl_add_u64 v[4:5], v[4:5], 0, s[8:9]
	s_add_i32 m0, s35, 0x1a000
	s_add_i32 s75, s35, 0x8000
	s_add_i32 s76, s35, 0xa000
	global_load_lds_dwordx4 v[4:5], off
	v_lshl_add_u64 v[0:1], v[0:1], 0, s[8:9]
	s_mov_b32 m0, s75
	s_add_u32 s4, s36, 0x40080
	global_load_lds_dwordx4 v[0:1], off
	v_lshl_add_u64 v[0:1], v[2:3], 0, s[8:9]
	s_mov_b32 m0, s76
	s_addc_u32 s5, s37, 0
	global_load_lds_dwordx4 v[0:1], off
	s_add_i32 m0, s35, 0x1c000
	v_lshl_add_u64 v[0:1], s[4:5], 0, v[130:131]
	global_load_lds_dwordx4 v[0:1], off
	v_lshl_add_u64 v[0:1], s[4:5], 0, v[134:135]
	s_add_i32 m0, s35, 0x1e000
	v_and_b32_e32 v2, 48, v8
	global_load_lds_dwordx4 v[0:1], off
	s_waitcnt vmcnt(8)
	s_barrier
	v_and_b32_e32 v0, 15, v8
	v_ashrrev_i32_e32 v1, 6, v8
	v_readlane_b32 s4, v254, 3
	v_lshl_or_b32 v0, v0, 6, v2
	v_lshlrev_b32_e32 v3, 2, v8
	v_lshl_add_u32 v2, v1, 10, s4
	v_readlane_b32 s4, v254, 5
	v_and_b32_e32 v3, 32, v3
	v_bitop3_b32 v2, v0, v2, v3 bitop3:0xde
	v_add_lshl_u32 v1, v1, s4, 10
	v_bitop3_b32 v144, v0, v1, v3 bitop3:0xde
	v_lshlrev_b32_e32 v0, 14, v12
	v_and_b32_e32 v0, 0xffff8000, v0
	v_lshl_add_u32 v0, v13, 11, v0
	v_and_b32_e32 v1, 1, v12
	v_lshl_or_b32 v0, v1, 6, v0
	v_lshl_add_u32 v136, v14, 1, v0
	v_lshlrev_b32_e32 v0, 14, v9
	v_and_b32_e32 v0, 0xffff8000, v0
	s_waitcnt vmcnt(6)
	s_cmpk_lt_u32 s3, 0x100
	v_lshl_add_u32 v0, v10, 11, v0
	v_and_b32_e32 v1, 1, v9
	s_cselect_b64 s[10:11], -1, 0
	s_lshl_b32 s4, s33, 4
	v_lshl_or_b32 v0, v1, 6, v0
	s_add_i32 s80, 0, 0x10000
	s_add_i32 s81, 0, 0x14000
	s_sext_i32_i8 s89, s6
	s_and_b32 s77, s4, 0x3fffffc0
	s_ashr_i32 s78, s56, 31
	s_mov_b32 s79, s56
	v_mov_b32_e32 v137, v131
	v_lshl_add_u32 v138, v11, 1, v0
	v_mov_b32_e32 v139, v131
	v_mov_b64_e32 v[140:141], 0x800
	v_mov_b64_e32 v[142:143], 0x7ff
	v_add_u32_e32 v145, s80, v144
	v_add_u32_e32 v146, s81, v144
	v_add_u32_e32 v147, 0, v2
	s_mov_b64 s[16:17], 0x100000
	s_mov_b32 s82, 0x100000
	s_mov_b64 s[18:19], 0x120000
	s_mov_b32 s83, 0x120000
	s_mov_b64 s[20:21], 0x140000
	s_mov_b32 s90, 0x140000
	s_mov_b64 s[22:23], 0x160000
	s_mov_b32 s91, 0x160000
	s_barrier
	s_waitcnt vmcnt(0)
	s_branch .LBB0_478

; #define PG8_STAGE(bufoff, gbase, voff) do { _Pragma("unroll") for (int _i = 0; _i < 2; ++_i) \
;         __builtin_amdgcn_global_load_lds((const unsigned*)((const char*)(gbase) + (voff)[_i]), (LAS unsigned*)(lds + (bufoff) + ldsw + _i * 8192), 16, 0, 0); } while (0)
; #define PG8_WAIT_V(n) asm volatile("s_waitcnt vmcnt(" #n ")" ::: "memory")
; #define PG8_BAR __builtin_amdgcn_s_barrier()
; template <class Epi>
; __device__ __forceinline__ void gemm_phase(LAS unsigned char* lds, const Gemm g, const StaticOrder& S, const Epi& E, const int wid) {
;     ...
;     for (int i = 0; i < 2; ++i) { int R, C; stage_rc(tid * 16 + i * 8192, R, C); const int Rb = Epi::PERM ? ((R & ~31) + perm32(R & 31)) : R;
;         voffA[i] = (unsigned)(R * lda + C) * 2u; voffB[i] = (unsigned)(Rb * K + C) * 2u; }
;     const size_t kstep = (size_t)(BK * 2);
;     const size_t hsA = (size_t)HALF * lda * 2, hsB = (size_t)HALF * K * 2;
;     const size_t tsA = 2 * hsA, tsB = 2 * hsB;
;     const unsigned ldsw = (unsigned)wid * 1024u;
;     const int aoff = lds_byte(wr * 64 + fr, fq * 8), boff = lds_byte(wc * 32 + fr, fq * 8);
;     ...
;     PG8_STAGE(PG8_SB(0, 0), cB, voffB); PG8_STAGE(PG8_SB(0, 1), cB + hsB, voffB); PG8_STAGE(PG8_SA(0, 0), cA, voffA); PG8_STAGE(PG8_SA(0, 1), cA + hsA, voffA);
;     if (wr == 1) PG8_BAR;
;     PG8_WAIT_V(2); PG8_BAR;
;     PG8_STAGE(PG8_SB(1, 0), cB + kstep, voffB); PG8_STAGE(PG8_SA(1, 0), cA + kstep, voffA); PG8_STAGE(PG8_SB(1, 1), cB + hsB + kstep, voffB);
;     PG8_WAIT_V(6); PG8_BAR;
.LBB0_545:
	s_mov_b64 s[10:11], 0x80
	s_add_i32 m0, s27, 0x18000
	v_lshl_add_u64 v[6:7], v[6:7], 0, s[10:11]
	global_load_lds_dwordx4 v[6:7], off
	v_lshl_add_u64 v[4:5], v[4:5], 0, s[10:11]
	s_add_i32 m0, s27, 0x1a000
	s_add_i32 s64, s27, 0x8000
	s_add_i32 s65, s27, 0xa000
	global_load_lds_dwordx4 v[4:5], off
	v_lshl_add_u64 v[0:1], v[0:1], 0, s[10:11]
	s_mov_b32 m0, s64
	s_add_u32 s4, s28, 0x100080
	global_load_lds_dwordx4 v[0:1], off
	v_lshl_add_u64 v[0:1], v[2:3], 0, s[10:11]
	s_mov_b32 m0, s65
	s_addc_u32 s5, s29, 0
	global_load_lds_dwordx4 v[0:1], off
	s_add_i32 m0, s27, 0x1c000
	v_lshl_add_u64 v[0:1], s[4:5], 0, v[194:195]
	global_load_lds_dwordx4 v[0:1], off
	v_lshl_add_u64 v[0:1], s[4:5], 0, v[198:199]
	s_add_i32 m0, s27, 0x1e000
	v_and_b32_e32 v2, 48, v8
	global_load_lds_dwordx4 v[0:1], off
	s_waitcnt vmcnt(8)
	s_barrier
	v_and_b32_e32 v0, 15, v8
	v_ashrrev_i32_e32 v1, 6, v8
	v_readlane_b32 s1, v254, 3
	v_lshl_or_b32 v0, v0, 6, v2
	v_lshlrev_b32_e32 v3, 2, v8
	v_lshl_add_u32 v2, v1, 10, s1
	v_readlane_b32 s1, v254, 5
	v_and_b32_e32 v3, 32, v3
	v_bitop3_b32 v2, v0, v2, v3 bitop3:0xde
	v_add_lshl_u32 v1, v1, s1, 10
	v_bitop3_b32 v240, v0, v1, v3 bitop3:0xde
	v_lshlrev_b32_e32 v0, 16, v12
	v_and_b32_e32 v0, 0xfffe0000, v0
	v_lshl_add_u32 v0, v13, 13, v0
	v_and_b32_e32 v1, 1, v12
	v_lshl_or_b32 v0, v1, 6, v0
	v_lshl_add_u32 v200, v14, 1, v0
	v_lshlrev_b32_e32 v0, 16, v9
	v_and_b32_e32 v0, 0xfffe0000, v0
	s_waitcnt vmcnt(6)
	s_cmpk_lt_u32 s3, 0x100
	v_lshl_add_u32 v0, v10, 13, v0
	v_and_b32_e32 v1, 1, v9
	s_cselect_b64 s[16:17], -1, 0
	s_lshl_b32 s1, s33, 4
	v_lshl_or_b32 v0, v1, 6, v0
	s_add_i32 s76, 0, 0x10000
	s_add_i32 s77, 0, 0x14000
	s_and_b32 s66, s1, 0x3fffffc0
	s_ashr_i32 s67, s56, 31
	s_mov_b32 s74, s56
	s_ashr_i32 s75, s2, 31
	v_mov_b32_e32 v201, v195
	v_lshl_add_u32 v202, v11, 1, v0
	v_mov_b32_e32 v203, v195
	v_add_u32_e32 v241, s76, v240
	v_add_u32_e32 v242, s77, v240
	v_add_u32_e32 v243, 0, v2
	v_mov_b32_e32 v245, 0x358637bd
	v_mbcnt_hi_u32_b32 v246, -1, v244
	s_barrier
	s_branch .LBB0_548

; #define PG8_STAGE(bufoff, gbase, voff) do { _Pragma("unroll") for (int _i = 0; _i < 2; ++_i) \
;         __builtin_amdgcn_global_load_lds((const unsigned*)((const char*)(gbase) + (voff)[_i]), (LAS unsigned*)(lds + (bufoff) + ldsw + _i * 8192), 16, 0, 0); } while (0)
; #define PG8_WAIT_V(n) asm volatile("s_waitcnt vmcnt(" #n ")" ::: "memory")
; #define PG8_BAR __builtin_amdgcn_s_barrier()
; template <class Epi>
; __device__ __forceinline__ void gemm_phase(LAS unsigned char* lds, const Gemm g, const StaticOrder& S, const Epi& E, const int wid) {
;     ...
;     for (int i = 0; i < 2; ++i) { int R, C; stage_rc(tid * 16 + i * 8192, R, C); const int Rb = Epi::PERM ? ((R & ~31) + perm32(R & 31)) : R;
;         voffA[i] = (unsigned)(R * lda + C) * 2u; voffB[i] = (unsigned)(Rb * K + C) * 2u; }
;     const size_t kstep = (size_t)(BK * 2);
;     const size_t hsA = (size_t)HALF * lda * 2, hsB = (size_t)HALF * K * 2;
;     const size_t tsA = 2 * hsA, tsB = 2 * hsB;
;     const unsigned ldsw = (unsigned)wid * 1024u;
;     const int aoff = lds_byte(wr * 64 + fr, fq * 8), boff = lds_byte(wc * 32 + fr, fq * 8);
;     ...
;     PG8_STAGE(PG8_SB(0, 0), cB, voffB); PG8_STAGE(PG8_SB(0, 1), cB + hsB, voffB); PG8_STAGE(PG8_SA(0, 0), cA, voffA); PG8_STAGE(PG8_SA(0, 1), cA + hsA, voffA);
;     if (wr == 1) PG8_BAR;
;     PG8_WAIT_V(2); PG8_BAR;
;     PG8_STAGE(PG8_SB(1, 0), cB + kstep, voffB); PG8_STAGE(PG8_SA(1, 0), cA + kstep, voffA); PG8_STAGE(PG8_SB(1, 1), cB + hsB + kstep, voffB);
;     PG8_WAIT_V(6); PG8_BAR;
.LBB0_629:
	s_mov_b64 s[8:9], 0x80
	s_add_i32 m0, s19, 0x18000
	v_lshl_add_u64 v[6:7], v[6:7], 0, s[8:9]
	global_load_lds_dwordx4 v[6:7], off
	v_lshl_add_u64 v[4:5], v[4:5], 0, s[8:9]
	s_add_i32 m0, s19, 0x1a000
	s_add_i32 s81, s19, 0x8000
	s_add_i32 s82, s19, 0xa000
	global_load_lds_dwordx4 v[4:5], off
	v_lshl_add_u64 v[0:1], v[0:1], 0, s[8:9]
	s_mov_b32 m0, s81
	s_add_u32 s4, s22, 0x10080
	global_load_lds_dwordx4 v[0:1], off
	v_lshl_add_u64 v[0:1], v[2:3], 0, s[8:9]
	s_mov_b32 m0, s82
	s_addc_u32 s5, s23, 0
	global_load_lds_dwordx4 v[0:1], off
	s_add_i32 m0, s19, 0x1c000
	v_lshl_add_u64 v[0:1], s[4:5], 0, v[130:131]
	global_load_lds_dwordx4 v[0:1], off
	v_lshl_add_u64 v[0:1], s[4:5], 0, v[134:135]
	s_add_i32 m0, s19, 0x1e000
	v_and_b32_e32 v2, 48, v8
	global_load_lds_dwordx4 v[0:1], off
	s_waitcnt vmcnt(8)
	s_barrier
	v_and_b32_e32 v0, 15, v8
	v_ashrrev_i32_e32 v1, 6, v8
	v_readlane_b32 s4, v254, 3
	v_lshl_or_b32 v0, v0, 6, v2
	v_lshlrev_b32_e32 v3, 2, v8
	v_lshl_add_u32 v2, v1, 10, s4
	v_readlane_b32 s4, v254, 5
	v_and_b32_e32 v3, 32, v3
	s_waitcnt vmcnt(6)
	s_cmpk_lt_u32 s3, 0x100
	v_add_lshl_u32 v1, v1, s4, 10
	v_bitop3_b32 v2, v0, v2, v3 bitop3:0xde
	v_bitop3_b32 v140, v0, v1, v3 bitop3:0xde
	s_cselect_b64 s[10:11], -1, 0
	s_lshl_b32 s4, s33, 4
	s_add_i32 s91, 0, 0x10000
	s_add_i32 s92, 0, 0x14000
	s_sext_i32_i8 s93, s6
	s_and_b32 s83, s4, 0x3fffffc0
	s_ashr_i32 s89, s56, 31
	s_mov_b32 s90, s56
	v_mov_b64_e32 v[136:137], 0x200
	v_mov_b64_e32 v[138:139], 0x1ff
	v_add_u32_e32 v141, s91, v140
	v_add_u32_e32 v142, s92, v140
	v_add_u32_e32 v143, 0, v2
	s_barrier
	s_branch .LBB0_632

; #define PG8_STAGE(bufoff, gbase, voff) do { _Pragma("unroll") for (int _i = 0; _i < 2; ++_i) \
;         __builtin_amdgcn_global_load_lds((const unsigned*)((const char*)(gbase) + (voff)[_i]), (LAS unsigned*)(lds + (bufoff) + ldsw + _i * 8192), 16, 0, 0); } while (0)
; #define PG8_WAIT_V(n) asm volatile("s_waitcnt vmcnt(" #n ")" ::: "memory")
; #define PG8_BAR __builtin_amdgcn_s_barrier()
; template <class Epi>
; __device__ __forceinline__ void gemm_phase(LAS unsigned char* lds, const Gemm g, const StaticOrder& S, const Epi& E, const int wid) {
;     ...
;     for (int i = 0; i < 2; ++i) { int R, C; stage_rc(tid * 16 + i * 8192, R, C); const int Rb = Epi::PERM ? ((R & ~31) + perm32(R & 31)) : R;
;         voffA[i] = (unsigned)(R * lda + C) * 2u; voffB[i] = (unsigned)(Rb * K + C) * 2u; }
;     const size_t kstep = (size_t)(BK * 2);
;     const size_t hsA = (size_t)HALF * lda * 2, hsB = (size_t)HALF * K * 2;
;     const size_t tsA = 2 * hsA, tsB = 2 * hsB;
;     const unsigned ldsw = (unsigned)wid * 1024u;
;     const int aoff = lds_byte(wr * 64 + fr, fq * 8), boff = lds_byte(wc * 32 + fr, fq * 8);
;     ...
;     PG8_STAGE(PG8_SB(0, 0), cB, voffB); PG8_STAGE(PG8_SB(0, 1), cB + hsB, voffB); PG8_STAGE(PG8_SA(0, 0), cA, voffA); PG8_STAGE(PG8_SA(0, 1), cA + hsA, voffA);
;     if (wr == 1) PG8_BAR;
;     PG8_WAIT_V(2); PG8_BAR;
;     PG8_STAGE(PG8_SB(1, 0), cB + kstep, voffB); PG8_STAGE(PG8_SA(1, 0), cA + kstep, voffA); PG8_STAGE(PG8_SB(1, 1), cB + hsB + kstep, voffB);
;     PG8_WAIT_V(6); PG8_BAR;
.LBB0_655:
	s_mov_b64 s[16:17], 0x80
	s_add_i32 m0, s38, 0x18000
	v_lshl_add_u64 v[6:7], v[6:7], 0, s[16:17]
	global_load_lds_dwordx4 v[6:7], off
	v_lshl_add_u64 v[4:5], v[4:5], 0, s[16:17]
	s_add_i32 m0, s38, 0x1a000
	s_add_i32 s65, s38, 0x8000
	s_add_i32 s66, s38, 0xa000
	global_load_lds_dwordx4 v[4:5], off
	v_lshl_add_u64 v[0:1], v[0:1], 0, s[16:17]
	s_mov_b32 m0, s65
	s_add_u32 s4, s28, 0x40080
	global_load_lds_dwordx4 v[0:1], off
	v_lshl_add_u64 v[0:1], v[2:3], 0, s[16:17]
	s_mov_b32 m0, s66
	s_addc_u32 s5, s29, 0
	global_load_lds_dwordx4 v[0:1], off
	s_add_i32 m0, s38, 0x1c000
	v_lshl_add_u64 v[0:1], s[4:5], 0, v[154:155]
	global_load_lds_dwordx4 v[0:1], off
	v_lshl_add_u64 v[0:1], s[4:5], 0, v[158:159]
	s_add_i32 m0, s38, 0x1e000
	v_and_b32_e32 v2, 48, v8
	global_load_lds_dwordx4 v[0:1], off
	s_waitcnt vmcnt(8)
	s_barrier
	v_and_b32_e32 v0, 15, v8
	v_ashrrev_i32_e32 v1, 6, v8
	v_readlane_b32 s4, v254, 3
	v_lshl_or_b32 v0, v0, 6, v2
	v_lshlrev_b32_e32 v3, 2, v8
	v_lshl_add_u32 v2, v1, 10, s4
	v_readlane_b32 s4, v254, 5
	v_and_b32_e32 v3, 32, v3
	v_bitop3_b32 v2, v0, v2, v3 bitop3:0xde
	v_add_lshl_u32 v1, v1, s4, 10
	v_bitop3_b32 v182, v0, v1, v3 bitop3:0xde
	v_lshlrev_b32_e32 v0, 14, v12
	v_and_b32_e32 v0, 0xffff8000, v0
	v_lshl_add_u32 v0, v13, 11, v0
	v_and_b32_e32 v1, 1, v12
	v_lshl_or_b32 v0, v1, 6, v0
	v_lshl_add_u32 v160, v14, 1, v0
	v_lshlrev_b32_e32 v0, 14, v9
	v_and_b32_e32 v0, 0xffff8000, v0
	s_waitcnt vmcnt(6)
	s_cmpk_lt_u32 s3, 0x100
	v_lshl_add_u32 v0, v10, 11, v0
	v_and_b32_e32 v1, 1, v9
	s_cselect_b64 s[18:19], -1, 0
	s_lshl_b32 s4, s33, 4
	v_lshl_or_b32 v0, v1, 6, v0
	s_add_i32 s77, 0, 0x10000
	s_add_i32 s78, 0, 0x14000
	s_and_b32 s67, s4, 0x3fffffc0
	s_ashr_i32 s74, s56, 31
	s_mov_b32 s75, s56
	s_ashr_i32 s76, s2, 31
	v_mov_b32_e32 v161, v155
	v_lshl_add_u32 v162, v11, 1, v0
	v_mov_b32_e32 v163, v155
	v_mov_b64_e32 v[164:165], 0x200
	v_mov_b64_e32 v[166:167], 0x1ff
	v_add_u32_e32 v183, s77, v182
	v_add_u32_e32 v184, s78, v182
	v_add_u32_e32 v185, 0, v2
	v_mov_b32_e32 v186, 0x358637bd
	v_mbcnt_hi_u32_b32 v187, -1, v244
	s_barrier
	s_branch .LBB0_658

; #define PG8_STAGE(bufoff, gbase, voff) do { _Pragma("unroll") for (int _i = 0; _i < 2; ++_i) \
;         __builtin_amdgcn_global_load_lds((const unsigned*)((const char*)(gbase) + (voff)[_i]), (LAS unsigned*)(lds + (bufoff) + ldsw + _i * 8192), 16, 0, 0); } while (0)
; #define PG8_WAIT_V(n) asm volatile("s_waitcnt vmcnt(" #n ")" ::: "memory")
; #define PG8_BAR __builtin_amdgcn_s_barrier()
; template <class Epi>
; __device__ __forceinline__ void gemm_phase(LAS unsigned char* lds, const Gemm g, const StaticOrder& S, const Epi& E, const int wid) {
;     ...
;     for (int i = 0; i < 2; ++i) { int R, C; stage_rc(tid * 16 + i * 8192, R, C); const int Rb = Epi::PERM ? ((R & ~31) + perm32(R & 31)) : R;
;         voffA[i] = (unsigned)(R * lda + C) * 2u; voffB[i] = (unsigned)(Rb * K + C) * 2u; }
;     const size_t kstep = (size_t)(BK * 2);
;     const size_t hsA = (size_t)HALF * lda * 2, hsB = (size_t)HALF * K * 2;
;     const size_t tsA = 2 * hsA, tsB = 2 * hsB;
;     const unsigned ldsw = (unsigned)wid * 1024u;
;     const int aoff = lds_byte(wr * 64 + fr, fq * 8), boff = lds_byte(wc * 32 + fr, fq * 8);
;     ...
;     PG8_STAGE(PG8_SB(0, 0), cB, voffB); PG8_STAGE(PG8_SB(0, 1), cB + hsB, voffB); PG8_STAGE(PG8_SA(0, 0), cA, voffA); PG8_STAGE(PG8_SA(0, 1), cA + hsA, voffA);
;     if (wr == 1) PG8_BAR;
;     PG8_WAIT_V(2); PG8_BAR;
;     PG8_STAGE(PG8_SB(1, 0), cB + kstep, voffB); PG8_STAGE(PG8_SA(1, 0), cA + kstep, voffA); PG8_STAGE(PG8_SB(1, 1), cB + hsB + kstep, voffB);
;     PG8_WAIT_V(6); PG8_BAR;
.LBB0_769:
	s_add_u32 s66, s54, 0xc0000
	s_mov_b64 s[16:17], 0x80
	s_addc_u32 s67, s55, 0
	s_add_i32 m0, s9, 0x18000
	v_lshl_add_u64 v[6:7], v[6:7], 0, s[16:17]
	global_load_lds_dwordx4 v[6:7], off
	v_lshl_add_u64 v[4:5], v[4:5], 0, s[16:17]
	s_add_i32 m0, s9, 0x1a000
	s_add_i32 s74, s9, 0x8000
	s_add_i32 s75, s9, 0xa000
	global_load_lds_dwordx4 v[4:5], off
	v_lshl_add_u64 v[0:1], v[0:1], 0, s[16:17]
	s_mov_b32 m0, s74
	s_add_u32 s4, s34, 0x40080
	global_load_lds_dwordx4 v[0:1], off
	v_lshl_add_u64 v[0:1], v[2:3], 0, s[16:17]
	s_mov_b32 m0, s75
	s_addc_u32 s5, s35, 0
	global_load_lds_dwordx4 v[0:1], off
	s_add_i32 m0, s9, 0x1c000
	v_lshl_add_u64 v[0:1], s[4:5], 0, v[130:131]
	global_load_lds_dwordx4 v[0:1], off
	v_lshl_add_u64 v[0:1], s[4:5], 0, v[134:135]
	s_add_i32 m0, s9, 0x1e000
	v_and_b32_e32 v2, 48, v8
	global_load_lds_dwordx4 v[0:1], off
	s_waitcnt vmcnt(8)
	s_barrier
	v_and_b32_e32 v0, 15, v8
	v_ashrrev_i32_e32 v1, 6, v8
	v_readlane_b32 s1, v254, 3
	v_lshl_or_b32 v0, v0, 6, v2
	v_lshlrev_b32_e32 v3, 2, v8
	v_lshl_add_u32 v2, v1, 10, s1
	v_readlane_b32 s1, v254, 5
	v_and_b32_e32 v3, 32, v3
	v_bitop3_b32 v2, v0, v2, v3 bitop3:0xde
	v_add_lshl_u32 v1, v1, s1, 10
	v_bitop3_b32 v150, v0, v1, v3 bitop3:0xde
	v_lshlrev_b32_e32 v0, 14, v9
	v_and_b32_e32 v0, 0xffff8000, v0
	v_lshl_add_u32 v0, v10, 11, v0
	v_and_b32_e32 v1, 1, v9
	s_cmpk_lt_u32 s3, 0x100
	v_lshl_or_b32 v0, v1, 6, v0
	s_cselect_b64 s[18:19], -1, 0
	s_lshl_b32 s1, s33, 4
	v_lshl_add_u32 v136, v11, 1, v0
	v_lshlrev_b32_e32 v0, 14, v12
	s_and_b32 s76, s1, 0x3fffffc0
	s_ashr_i32 s77, s56, 31
	s_ashr_i32 s79, s2, 31
	v_and_b32_e32 v0, 0xffff8000, v0
	s_waitcnt vmcnt(6)
	s_cmp_eq_u64 s[58:59], 0
	v_lshl_add_u32 v0, v13, 11, v0
	v_and_b32_e32 v1, 1, v12
	s_cselect_b64 s[20:21], -1, 0
	v_lshl_or_b32 v0, v1, 6, v0
	s_add_i32 s80, 0, 0x10000
	s_add_i32 s81, 0, 0x14000
	s_mov_b32 s78, s56
	v_mov_b32_e32 v137, v131
	v_lshl_add_u32 v138, v14, 1, v0
	v_mov_b32_e32 v139, v131
	v_mov_b64_e32 v[140:141], 0x180
	v_mov_b64_e32 v[142:143], 0x17f
	v_add_u32_e32 v151, s80, v150
	v_add_u32_e32 v152, s81, v150
	v_add_u32_e32 v153, 0, v2
	v_mbcnt_hi_u32_b32 v154, -1, v244
	v_mov_b32_e32 v155, 0x358637bd
	s_movk_i32 s82, 0x600
	s_barrier
	s_branch .LBB0_772

; #define PG8_STAGE(bufoff, gbase, voff) do { _Pragma("unroll") for (int _i = 0; _i < 2; ++_i) \
;         __builtin_amdgcn_global_load_lds((const unsigned*)((const char*)(gbase) + (voff)[_i]), (LAS unsigned*)(lds + (bufoff) + ldsw + _i * 8192), 16, 0, 0); } while (0)
; #define PG8_WAIT_V(n) asm volatile("s_waitcnt vmcnt(" #n ")" ::: "memory")
; #define PG8_BAR __builtin_amdgcn_s_barrier()
; template <class Epi>
; __device__ __forceinline__ void gemm_phase(LAS unsigned char* lds, const Gemm g, const StaticOrder& S, const Epi& E, const int wid) {
;     ...
;     for (int i = 0; i < 2; ++i) { int R, C; stage_rc(tid * 16 + i * 8192, R, C); const int Rb = Epi::PERM ? ((R & ~31) + perm32(R & 31)) : R;
;         voffA[i] = (unsigned)(R * lda + C) * 2u; voffB[i] = (unsigned)(Rb * K + C) * 2u; }
;     const size_t kstep = (size_t)(BK * 2);
;     const size_t hsA = (size_t)HALF * lda * 2, hsB = (size_t)HALF * K * 2;
;     const size_t tsA = 2 * hsA, tsB = 2 * hsB;
;     const unsigned ldsw = (unsigned)wid * 1024u;
;     const int aoff = lds_byte(wr * 64 + fr, fq * 8), boff = lds_byte(wc * 32 + fr, fq * 8);
;     ...
;     PG8_STAGE(PG8_SB(0, 0), cB, voffB); PG8_STAGE(PG8_SB(0, 1), cB + hsB, voffB); PG8_STAGE(PG8_SA(0, 0), cA, voffA); PG8_STAGE(PG8_SA(0, 1), cA + hsA, voffA);
;     if (wr == 1) PG8_BAR;
;     PG8_WAIT_V(2); PG8_BAR;
;     PG8_STAGE(PG8_SB(1, 0), cB + kstep, voffB); PG8_STAGE(PG8_SA(1, 0), cA + kstep, voffA); PG8_STAGE(PG8_SB(1, 1), cB + hsB + kstep, voffB);
;     PG8_WAIT_V(6); PG8_BAR;
.LBB0_861:
	s_mov_b64 s[10:11], 0x80
	s_add_i32 m0, s34, 0x18000
	v_lshl_add_u64 v[6:7], v[6:7], 0, s[10:11]
	global_load_lds_dwordx4 v[6:7], off
	v_lshl_add_u64 v[4:5], v[4:5], 0, s[10:11]
	s_add_i32 m0, s34, 0x1a000
	s_add_i32 s39, s34, 0x8000
	s_add_i32 s62, s34, 0xa000
	global_load_lds_dwordx4 v[4:5], off
	v_lshl_add_u64 v[0:1], v[0:1], 0, s[10:11]
	s_mov_b32 m0, s39
	s_add_u32 s6, s22, 0x18080
	global_load_lds_dwordx4 v[0:1], off
	v_lshl_add_u64 v[0:1], v[2:3], 0, s[10:11]
	s_mov_b32 m0, s62
	s_addc_u32 s7, s23, 0
	global_load_lds_dwordx4 v[0:1], off
	s_add_i32 m0, s34, 0x1c000
	v_lshl_add_u64 v[0:1], s[6:7], 0, v[132:133]
	global_load_lds_dwordx4 v[0:1], off
	v_lshl_add_u64 v[0:1], s[6:7], 0, v[128:129]
	s_add_i32 m0, s34, 0x1e000
	s_sext_i32_i8 s78, s5
	global_load_lds_dwordx4 v[0:1], off
	s_waitcnt vmcnt(8)
	s_barrier
	v_and_b32_e32 v0, 15, v10
	v_ashrrev_i32_e32 v1, 6, v10
	v_and_b32_e32 v2, 48, v10
	v_readlane_b32 s5, v254, 3
	v_lshl_or_b32 v0, v0, 6, v2
	v_lshlrev_b32_e32 v3, 2, v10
	v_lshl_add_u32 v2, v1, 10, s5
	v_readlane_b32 s5, v254, 5
	s_cmpk_lt_u32 s3, 0x100
	v_and_b32_e32 v3, 32, v3
	v_add_lshl_u32 v1, v1, s5, 10
	s_cselect_b64 s[16:17], -1, 0
	s_lshl_b32 s5, s33, 4
	v_bitop3_b32 v2, v0, v2, v3 bitop3:0xde
	v_bitop3_b32 v144, v0, v1, v3 bitop3:0xde
	s_and_b32 s63, s5, 0x3fffffc0
	v_lshrrev_b32_e32 v1, 1, v8
	v_mul_lo_u32 v0, v9, s4
	s_movk_i32 s5, 0x3000
	v_mad_u64_u32 v[0:1], s[6:7], v1, s5, v[0:1]
	v_or_b32_e32 v0, v0, v11
	v_add_lshl_u32 v0, v0, v12, 1
	v_mov_b32_e32 v1, v133
	s_mov_b64 s[6:7], 0x30080
	v_lshl_add_u64 v[136:137], v[0:1], 0, s[6:7]
	v_lshrrev_b32_e32 v1, 1, v13
	v_mul_lo_u32 v0, v14, s4
	v_mad_u64_u32 v[0:1], s[4:5], v1, s5, v[0:1]
	s_waitcnt vmcnt(6)
	v_or_b32_e32 v0, v0, v15
	v_add_lshl_u32 v0, v0, v16, 1
	v_mov_b32_e32 v1, v133
	s_add_i32 s66, 0, 0x10000
	s_add_i32 s67, 0, 0x14000
	s_ashr_i32 s64, s56, 31
	s_mov_b32 s65, s56
	v_lshl_add_u64 v[138:139], v[0:1], 0, s[6:7]
	v_mov_b64_e32 v[140:141], 0x300
	v_mov_b64_e32 v[142:143], 0x2ff
	v_add_u32_e32 v145, s66, v144
	v_add_u32_e32 v146, s67, v144
	v_add_u32_e32 v147, 0, v2
	s_movk_i32 s74, 0xc00
	s_barrier
	s_branch .LBB0_864

; #define PG8_STAGE(bufoff, gbase, voff) do { _Pragma("unroll") for (int _i = 0; _i < 2; ++_i) \
;         __builtin_amdgcn_global_load_lds((const unsigned*)((const char*)(gbase) + (voff)[_i]), (LAS unsigned*)(lds + (bufoff) + ldsw + _i * 8192), 16, 0, 0); } while (0)
; #define PG8_WAIT_V(n) asm volatile("s_waitcnt vmcnt(" #n ")" ::: "memory")
; #define PG8_BAR __builtin_amdgcn_s_barrier()
; template <class Epi>
; __device__ __forceinline__ void gemm_phase(LAS unsigned char* lds, const Gemm g, const StaticOrder& S, const Epi& E, const int wid) {
;     ...
;     for (int i = 0; i < 2; ++i) { int R, C; stage_rc(tid * 16 + i * 8192, R, C); const int Rb = Epi::PERM ? ((R & ~31) + perm32(R & 31)) : R;
;         voffA[i] = (unsigned)(R * lda + C) * 2u; voffB[i] = (unsigned)(Rb * K + C) * 2u; }
;     const size_t kstep = (size_t)(BK * 2);
;     const size_t hsA = (size_t)HALF * lda * 2, hsB = (size_t)HALF * K * 2;
;     const size_t tsA = 2 * hsA, tsB = 2 * hsB;
;     const unsigned ldsw = (unsigned)wid * 1024u;
;     const int aoff = lds_byte(wr * 64 + fr, fq * 8), boff = lds_byte(wc * 32 + fr, fq * 8);
;     ...
;     PG8_STAGE(PG8_SB(0, 0), cB, voffB); PG8_STAGE(PG8_SB(0, 1), cB + hsB, voffB); PG8_STAGE(PG8_SA(0, 0), cA, voffA); PG8_STAGE(PG8_SA(0, 1), cA + hsA, voffA);
;     if (wr == 1) PG8_BAR;
;     PG8_WAIT_V(2); PG8_BAR;
;     PG8_STAGE(PG8_SB(1, 0), cB + kstep, voffB); PG8_STAGE(PG8_SA(1, 0), cA + kstep, voffA); PG8_STAGE(PG8_SB(1, 1), cB + hsB + kstep, voffB);
;     PG8_WAIT_V(6); PG8_BAR;
.LBB0_881:
	s_mov_b64 s[10:11], 0x80
	s_add_i32 m0, s76, 0x18000
	v_lshl_add_u64 v[6:7], v[6:7], 0, s[10:11]
	global_load_lds_dwordx4 v[6:7], off
	v_lshl_add_u64 v[4:5], v[4:5], 0, s[10:11]
	s_add_i32 m0, s76, 0x1a000
	s_add_i32 s81, s76, 0x8000
	s_add_i32 s82, s76, 0xa000
	global_load_lds_dwordx4 v[4:5], off
	v_lshl_add_u64 v[0:1], v[0:1], 0, s[10:11]
	s_mov_b32 m0, s81
	s_add_u32 s4, s24, 0x10080
	global_load_lds_dwordx4 v[0:1], off
	v_lshl_add_u64 v[0:1], v[2:3], 0, s[10:11]
	s_mov_b32 m0, s82
	s_addc_u32 s5, s25, 0
	global_load_lds_dwordx4 v[0:1], off
	s_add_i32 m0, s76, 0x1c000
	v_lshl_add_u64 v[0:1], s[4:5], 0, v[132:133]
	global_load_lds_dwordx4 v[0:1], off
	v_lshl_add_u64 v[0:1], s[4:5], 0, v[128:129]
	s_add_i32 m0, s76, 0x1e000
	v_and_b32_e32 v2, 48, v8
	global_load_lds_dwordx4 v[0:1], off
	s_waitcnt vmcnt(8)
	s_barrier
	v_and_b32_e32 v0, 15, v8
	v_ashrrev_i32_e32 v1, 6, v8
	v_readlane_b32 s4, v254, 3
	v_lshl_or_b32 v0, v0, 6, v2
	v_lshlrev_b32_e32 v3, 2, v8
	v_lshl_add_u32 v2, v1, 10, s4
	v_readlane_b32 s4, v254, 5
	v_and_b32_e32 v3, 32, v3
	s_waitcnt vmcnt(6)
	s_cmpk_lt_u32 s3, 0x100
	v_add_lshl_u32 v1, v1, s4, 10
	v_bitop3_b32 v2, v0, v2, v3 bitop3:0xde
	v_bitop3_b32 v146, v0, v1, v3 bitop3:0xde
	s_cselect_b64 s[16:17], -1, 0
	s_lshl_b32 s4, s33, 4
	s_add_i32 s92, 0, 0x10000
	s_add_i32 s93, 0, 0x14000
	s_sext_i32_i8 s96, s6
	s_and_b32 s83, s4, 0x3fffffc0
	s_ashr_i32 s90, s56, 31
	s_mov_b32 s91, s56
	v_mov_b64_e32 v[136:137], 0x500
	v_mov_b64_e32 v[138:139], 0x4ff
	v_add_u32_e32 v147, s92, v146
	v_add_u32_e32 v148, s93, v146
	v_add_u32_e32 v149, 0, v2
	v_mov_b32_e32 v150, 0x358637bd
	s_movk_i32 s94, 0x1400
	s_barrier
	s_branch .LBB0_884

; #define PG8_STAGE(bufoff, gbase, voff) do { _Pragma("unroll") for (int _i = 0; _i < 2; ++_i) \
;         __builtin_amdgcn_global_load_lds((const unsigned*)((const char*)(gbase) + (voff)[_i]), (LAS unsigned*)(lds + (bufoff) + ldsw + _i * 8192), 16, 0, 0); } while (0)
; #define PG8_WAIT_V(n) asm volatile("s_waitcnt vmcnt(" #n ")" ::: "memory")
; #define PG8_BAR __builtin_amdgcn_s_barrier()
; template <class Epi>
; __device__ __forceinline__ void gemm_phase(LAS unsigned char* lds, const Gemm g, const StaticOrder& S, const Epi& E, const int wid) {
;     ...
;     for (int i = 0; i < 2; ++i) { int R, C; stage_rc(tid * 16 + i * 8192, R, C); const int Rb = Epi::PERM ? ((R & ~31) + perm32(R & 31)) : R;
;         voffA[i] = (unsigned)(R * lda + C) * 2u; voffB[i] = (unsigned)(Rb * K + C) * 2u; }
;     const size_t kstep = (size_t)(BK * 2);
;     const size_t hsA = (size_t)HALF * lda * 2, hsB = (size_t)HALF * K * 2;
;     const size_t tsA = 2 * hsA, tsB = 2 * hsB;
;     const unsigned ldsw = (unsigned)wid * 1024u;
;     const int aoff = lds_byte(wr * 64 + fr, fq * 8), boff = lds_byte(wc * 32 + fr, fq * 8);
;     ...
;     PG8_STAGE(PG8_SB(0, 0), cB, voffB); PG8_STAGE(PG8_SB(0, 1), cB + hsB, voffB); PG8_STAGE(PG8_SA(0, 0), cA, voffA); PG8_STAGE(PG8_SA(0, 1), cA + hsA, voffA);
;     if (wr == 1) PG8_BAR;
;     PG8_WAIT_V(2); PG8_BAR;
;     PG8_STAGE(PG8_SB(1, 0), cB + kstep, voffB); PG8_STAGE(PG8_SA(1, 0), cA + kstep, voffA); PG8_STAGE(PG8_SB(1, 1), cB + hsB + kstep, voffB);
;     PG8_WAIT_V(6); PG8_BAR;
.LBB0_1081:
	s_mov_b64 s[10:11], 0x80
	s_add_i32 m0, s27, 0x18000
	v_lshl_add_u64 v[6:7], v[6:7], 0, s[10:11]
	global_load_lds_dwordx4 v[6:7], off
	v_lshl_add_u64 v[4:5], v[4:5], 0, s[10:11]
	s_add_i32 m0, s27, 0x1a000
	s_add_i32 s58, s27, 0x8000
	s_add_i32 s59, s27, 0xa000
	global_load_lds_dwordx4 v[4:5], off
	v_lshl_add_u64 v[0:1], v[0:1], 0, s[10:11]
	s_mov_b32 m0, s58
	s_add_u32 s4, s28, 0x40080
	global_load_lds_dwordx4 v[0:1], off
	v_lshl_add_u64 v[0:1], v[2:3], 0, s[10:11]
	s_mov_b32 m0, s59
	s_addc_u32 s5, s29, 0
	global_load_lds_dwordx4 v[0:1], off
	s_add_i32 m0, s27, 0x1c000
	v_lshl_add_u64 v[0:1], s[4:5], 0, v[194:195]
	global_load_lds_dwordx4 v[0:1], off
	v_lshl_add_u64 v[0:1], s[4:5], 0, v[198:199]
	s_add_i32 m0, s27, 0x1e000
	v_and_b32_e32 v2, 48, v8
	global_load_lds_dwordx4 v[0:1], off
	s_waitcnt vmcnt(8)
	s_barrier
	v_and_b32_e32 v0, 15, v8
	v_ashrrev_i32_e32 v1, 6, v8
	v_readlane_b32 s1, v254, 3
	v_lshl_or_b32 v0, v0, 6, v2
	v_lshlrev_b32_e32 v3, 2, v8
	v_lshl_add_u32 v2, v1, 10, s1
	v_readlane_b32 s1, v254, 5
	v_and_b32_e32 v3, 32, v3
	v_bitop3_b32 v2, v0, v2, v3 bitop3:0xde
	v_add_lshl_u32 v1, v1, s1, 10
	v_bitop3_b32 v245, v0, v1, v3 bitop3:0xde
	v_lshlrev_b32_e32 v0, 14, v12
	v_and_b32_e32 v0, 0xffff8000, v0
	v_lshl_add_u32 v0, v13, 11, v0
	v_and_b32_e32 v1, 1, v12
	v_lshl_or_b32 v0, v1, 6, v0
	v_lshl_add_u32 v200, v14, 1, v0
	v_lshlrev_b32_e32 v0, 14, v9
	v_and_b32_e32 v0, 0xffff8000, v0
	s_waitcnt vmcnt(6)
	s_cmpk_lt_u32 s3, 0x100
	v_lshl_add_u32 v0, v10, 11, v0
	v_and_b32_e32 v1, 1, v9
	s_cselect_b64 s[16:17], -1, 0
	s_lshl_b32 s1, s33, 4
	v_lshl_or_b32 v0, v1, 6, v0
	s_add_i32 s64, 0, 0x10000
	s_add_i32 s65, 0, 0x14000
	s_and_b32 s60, s1, 0x3fffffc0
	s_ashr_i32 s61, s56, 31
	s_mov_b32 s62, s56
	s_ashr_i32 s63, s2, 31
	v_mov_b32_e32 v201, v195
	v_lshl_add_u32 v202, v11, 1, v0
	v_mov_b32_e32 v203, v195
	v_mov_b64_e32 v[204:205], 0x200
	v_mov_b64_e32 v[206:207], 0x1ff
	v_add_u32_e32 v246, s64, v245
	v_add_u32_e32 v247, s65, v245
	v_add_u32_e32 v248, 0, v2
	v_mbcnt_hi_u32_b32 v249, -1, v244
	s_barrier
	s_branch .LBB0_1084

; #define PG8_STAGE(bufoff, gbase, voff) do { _Pragma("unroll") for (int _i = 0; _i < 2; ++_i) \
;         __builtin_amdgcn_global_load_lds((const unsigned*)((const char*)(gbase) + (voff)[_i]), (LAS unsigned*)(lds + (bufoff) + ldsw + _i * 8192), 16, 0, 0); } while (0)
; #define PG8_WAIT_V(n) asm volatile("s_waitcnt vmcnt(" #n ")" ::: "memory")
; #define PG8_BAR __builtin_amdgcn_s_barrier()
; template <class Epi>
; __device__ __forceinline__ void gemm_phase(LAS unsigned char* lds, const Gemm g, const StaticOrder& S, const Epi& E, const int wid) {
;     ...
;     for (int i = 0; i < 2; ++i) { int R, C; stage_rc(tid * 16 + i * 8192, R, C); const int Rb = Epi::PERM ? ((R & ~31) + perm32(R & 31)) : R;
;         voffA[i] = (unsigned)(R * lda + C) * 2u; voffB[i] = (unsigned)(Rb * K + C) * 2u; }
;     const size_t kstep = (size_t)(BK * 2);
;     const size_t hsA = (size_t)HALF * lda * 2, hsB = (size_t)HALF * K * 2;
;     const size_t tsA = 2 * hsA, tsB = 2 * hsB;
;     const unsigned ldsw = (unsigned)wid * 1024u;
;     const int aoff = lds_byte(wr * 64 + fr, fq * 8), boff = lds_byte(wc * 32 + fr, fq * 8);
;     ...
;     PG8_STAGE(PG8_SB(0, 0), cB, voffB); PG8_STAGE(PG8_SB(0, 1), cB + hsB, voffB); PG8_STAGE(PG8_SA(0, 0), cA, voffA); PG8_STAGE(PG8_SA(0, 1), cA + hsA, voffA);
;     if (wr == 1) PG8_BAR;
;     PG8_WAIT_V(2); PG8_BAR;
;     PG8_STAGE(PG8_SB(1, 0), cB + kstep, voffB); PG8_STAGE(PG8_SA(1, 0), cA + kstep, voffA); PG8_STAGE(PG8_SB(1, 1), cB + hsB + kstep, voffB);
;     PG8_WAIT_V(6); PG8_BAR;
.LBB0_1165:
	s_mov_b64 s[6:7], 0x80
	s_add_i32 m0, s31, 0x18000
	v_lshl_add_u64 v[6:7], v[6:7], 0, s[6:7]
	global_load_lds_dwordx4 v[6:7], off
	v_lshl_add_u64 v[4:5], v[4:5], 0, s[6:7]
	s_add_i32 m0, s31, 0x1a000
	s_add_i32 s63, s31, 0x8000
	s_add_i32 s64, s31, 0xa000
	global_load_lds_dwordx4 v[4:5], off
	v_lshl_add_u64 v[0:1], v[0:1], 0, s[6:7]
	s_mov_b32 m0, s63
	s_add_u32 s8, s34, 0x40080
	global_load_lds_dwordx4 v[0:1], off
	v_lshl_add_u64 v[0:1], v[2:3], 0, s[6:7]
	s_mov_b32 m0, s64
	s_addc_u32 s9, s35, 0
	global_load_lds_dwordx4 v[0:1], off
	s_add_i32 m0, s31, 0x1c000
	v_lshl_add_u64 v[0:1], s[8:9], 0, v[130:131]
	global_load_lds_dwordx4 v[0:1], off
	v_lshl_add_u64 v[0:1], s[8:9], 0, v[134:135]
	s_add_i32 m0, s31, 0x1e000
	s_sext_i32_i8 s79, s4
	global_load_lds_dwordx4 v[0:1], off
	s_waitcnt vmcnt(8)
	s_barrier
	v_and_b32_e32 v0, 15, v8
	v_ashrrev_i32_e32 v1, 6, v8
	v_and_b32_e32 v2, 48, v8
	v_readlane_b32 s4, v254, 3
	v_lshl_or_b32 v0, v0, 6, v2
	v_lshlrev_b32_e32 v3, 2, v8
	v_lshl_add_u32 v2, v1, 10, s4
	v_readlane_b32 s4, v254, 5
	v_and_b32_e32 v3, 32, v3
	v_bitop3_b32 v2, v0, v2, v3 bitop3:0xde
	v_add_lshl_u32 v1, v1, s4, 10
	v_bitop3_b32 v144, v0, v1, v3 bitop3:0xde
	v_lshlrev_b32_e32 v0, 14, v12
	v_and_b32_e32 v0, 0xffff8000, v0
	v_lshl_add_u32 v0, v13, 11, v0
	v_and_b32_e32 v1, 1, v12
	v_lshl_or_b32 v0, v1, 6, v0
	v_lshl_add_u32 v136, v14, 1, v0
	v_lshlrev_b32_e32 v0, 14, v9
	v_and_b32_e32 v0, 0xffff8000, v0
	s_waitcnt vmcnt(6)
	s_cmpk_lt_u32 s3, 0x100
	v_lshl_add_u32 v0, v10, 11, v0
	v_and_b32_e32 v1, 1, v9
	s_cselect_b64 s[8:9], -1, 0
	s_lshl_b32 s4, s33, 4
	v_lshl_or_b32 v0, v1, 6, v0
	s_add_i32 s73, 0, 0x10000
	s_add_i32 s74, 0, 0x14000
	s_and_b32 s65, s4, 0x3fffffc0
	s_ashr_i32 s66, s56, 31
	s_mov_b32 s67, s56
	v_mov_b32_e32 v137, v131
	v_lshl_add_u32 v138, v11, 1, v0
	v_mov_b32_e32 v139, v131
	v_mov_b64_e32 v[140:141], 0x800
	v_mov_b64_e32 v[142:143], 0x7ff
	v_add_u32_e32 v145, s73, v144
	v_add_u32_e32 v146, s74, v144
	v_add_u32_e32 v147, 0, v2
	s_mov_b64 s[10:11], 0x100000
	s_mov_b32 s75, 0x100000
	s_mov_b64 s[16:17], 0x120000
	s_mov_b32 s76, 0x120000
	s_mov_b64 s[18:19], 0x140000
	s_mov_b32 s77, 0x140000
	s_mov_b64 s[20:21], 0x160000
	s_mov_b32 s78, 0x160000
	s_barrier
	s_branch .LBB0_1168

; #define PG8_STAGE(bufoff, gbase, voff) do { _Pragma("unroll") for (int _i = 0; _i < 2; ++_i) \
;         __builtin_amdgcn_global_load_lds((const unsigned*)((const char*)(gbase) + (voff)[_i]), (LAS unsigned*)(lds + (bufoff) + ldsw + _i * 8192), 16, 0, 0); } while (0)
; #define PG8_WAIT_V(n) asm volatile("s_waitcnt vmcnt(" #n ")" ::: "memory")
; #define PG8_BAR __builtin_amdgcn_s_barrier()
; template <class Epi>
; __device__ __forceinline__ void gemm_phase(LAS unsigned char* lds, const Gemm g, const StaticOrder& S, const Epi& E, const int wid) {
;     ...
;     for (int i = 0; i < 2; ++i) { int R, C; stage_rc(tid * 16 + i * 8192, R, C); const int Rb = Epi::PERM ? ((R & ~31) + perm32(R & 31)) : R;
;         voffA[i] = (unsigned)(R * lda + C) * 2u; voffB[i] = (unsigned)(Rb * K + C) * 2u; }
;     const size_t kstep = (size_t)(BK * 2);
;     const size_t hsA = (size_t)HALF * lda * 2, hsB = (size_t)HALF * K * 2;
;     const size_t tsA = 2 * hsA, tsB = 2 * hsB;
;     const unsigned ldsw = (unsigned)wid * 1024u;
;     const int aoff = lds_byte(wr * 64 + fr, fq * 8), boff = lds_byte(wc * 32 + fr, fq * 8);
;     ...
;     PG8_STAGE(PG8_SB(0, 0), cB, voffB); PG8_STAGE(PG8_SB(0, 1), cB + hsB, voffB); PG8_STAGE(PG8_SA(0, 0), cA, voffA); PG8_STAGE(PG8_SA(0, 1), cA + hsA, voffA);
;     if (wr == 1) PG8_BAR;
;     PG8_WAIT_V(2); PG8_BAR;
;     PG8_STAGE(PG8_SB(1, 0), cB + kstep, voffB); PG8_STAGE(PG8_SA(1, 0), cA + kstep, voffA); PG8_STAGE(PG8_SB(1, 1), cB + hsB + kstep, voffB);
;     PG8_WAIT_V(6); PG8_BAR;
.LBB0_1235:
	s_mov_b64 s[8:9], 0x80
	s_add_i32 m0, s25, 0x18000
	v_lshl_add_u64 v[6:7], v[6:7], 0, s[8:9]
	global_load_lds_dwordx4 v[6:7], off
	v_lshl_add_u64 v[4:5], v[4:5], 0, s[8:9]
	s_add_i32 m0, s25, 0x1a000
	s_add_i32 s58, s25, 0x8000
	s_add_i32 s59, s25, 0xa000
	global_load_lds_dwordx4 v[4:5], off
	v_lshl_add_u64 v[0:1], v[0:1], 0, s[8:9]
	s_mov_b32 m0, s58
	s_add_u32 s4, s26, 0x100080
	global_load_lds_dwordx4 v[0:1], off
	v_lshl_add_u64 v[0:1], v[2:3], 0, s[8:9]
	s_mov_b32 m0, s59
	s_addc_u32 s5, s27, 0
	global_load_lds_dwordx4 v[0:1], off
	s_add_i32 m0, s25, 0x1c000
	v_lshl_add_u64 v[0:1], s[4:5], 0, v[194:195]
	global_load_lds_dwordx4 v[0:1], off
	v_lshl_add_u64 v[0:1], s[4:5], 0, v[198:199]
	s_add_i32 m0, s25, 0x1e000
	v_and_b32_e32 v2, 48, v8
	global_load_lds_dwordx4 v[0:1], off
	s_waitcnt vmcnt(8)
	s_barrier
	v_and_b32_e32 v0, 15, v8
	v_ashrrev_i32_e32 v1, 6, v8
	v_readlane_b32 s1, v254, 3
	v_lshl_or_b32 v0, v0, 6, v2
	v_lshlrev_b32_e32 v3, 2, v8
	v_lshl_add_u32 v2, v1, 10, s1
	v_readlane_b32 s1, v254, 5
	v_and_b32_e32 v3, 32, v3
	v_bitop3_b32 v2, v0, v2, v3 bitop3:0xde
	v_add_lshl_u32 v1, v1, s1, 10
	v_bitop3_b32 v240, v0, v1, v3 bitop3:0xde
	v_lshlrev_b32_e32 v0, 16, v12
	v_and_b32_e32 v0, 0xfffe0000, v0
	v_lshl_add_u32 v0, v13, 13, v0
	v_and_b32_e32 v1, 1, v12
	v_lshl_or_b32 v0, v1, 6, v0
	v_lshl_add_u32 v200, v14, 1, v0
	v_lshlrev_b32_e32 v0, 16, v9
	v_and_b32_e32 v0, 0xfffe0000, v0
	s_waitcnt vmcnt(6)
	s_cmpk_lt_u32 s3, 0x100
	v_lshl_add_u32 v0, v10, 13, v0
	v_and_b32_e32 v1, 1, v9
	s_cselect_b64 s[10:11], -1, 0
	s_lshl_b32 s1, s33, 4
	v_lshl_or_b32 v0, v1, 6, v0
	s_add_i32 s64, 0, 0x10000
	s_add_i32 s65, 0, 0x14000
	s_and_b32 s60, s1, 0x3fffffc0
	s_ashr_i32 s61, s56, 31
	s_mov_b32 s62, s56
	s_ashr_i32 s63, s2, 31
	v_mov_b32_e32 v201, v195
	v_lshl_add_u32 v202, v11, 1, v0
	v_mov_b32_e32 v203, v195
	v_add_u32_e32 v241, s64, v240
	v_add_u32_e32 v242, s65, v240
	v_add_u32_e32 v243, 0, v2
	v_mov_b32_e32 v245, 0x358637bd
	v_mbcnt_hi_u32_b32 v244, -1, v244
	s_barrier
	s_branch .LBB0_1238

; #define PG8_STAGE(bufoff, gbase, voff) do { _Pragma("unroll") for (int _i = 0; _i < 2; ++_i) \
;         __builtin_amdgcn_global_load_lds((const unsigned*)((const char*)(gbase) + (voff)[_i]), (LAS unsigned*)(lds + (bufoff) + ldsw + _i * 8192), 16, 0, 0); } while (0)
; #define PG8_WAIT_V(n) asm volatile("s_waitcnt vmcnt(" #n ")" ::: "memory")
; #define PG8_BAR __builtin_amdgcn_s_barrier()
; template <class Epi>
; __device__ __forceinline__ void gemm_phase(LAS unsigned char* lds, const Gemm g, const StaticOrder& S, const Epi& E, const int wid) {
;     ...
;     for (int i = 0; i < 2; ++i) { int R, C; stage_rc(tid * 16 + i * 8192, R, C); const int Rb = Epi::PERM ? ((R & ~31) + perm32(R & 31)) : R;
;         voffA[i] = (unsigned)(R * lda + C) * 2u; voffB[i] = (unsigned)(Rb * K + C) * 2u; }
;     const size_t kstep = (size_t)(BK * 2);
;     const size_t hsA = (size_t)HALF * lda * 2, hsB = (size_t)HALF * K * 2;
;     const size_t tsA = 2 * hsA, tsB = 2 * hsB;
;     const unsigned ldsw = (unsigned)wid * 1024u;
;     const int aoff = lds_byte(wr * 64 + fr, fq * 8), boff = lds_byte(wc * 32 + fr, fq * 8);
;     ...
;     PG8_STAGE(PG8_SB(0, 0), cB, voffB); PG8_STAGE(PG8_SB(0, 1), cB + hsB, voffB); PG8_STAGE(PG8_SA(0, 0), cA, voffA); PG8_STAGE(PG8_SA(0, 1), cA + hsA, voffA);
;     if (wr == 1) PG8_BAR;
;     PG8_WAIT_V(2); PG8_BAR;
;     PG8_STAGE(PG8_SB(1, 0), cB + kstep, voffB); PG8_STAGE(PG8_SA(1, 0), cA + kstep, voffA); PG8_STAGE(PG8_SB(1, 1), cB + hsB + kstep, voffB);
;     PG8_WAIT_V(6); PG8_BAR;
.LBB0_1319:
	s_mov_b64 s[6:7], 0x80
	s_add_i32 m0, s21, 0x18000
	v_lshl_add_u64 v[6:7], v[6:7], 0, s[6:7]
	global_load_lds_dwordx4 v[6:7], off
	v_lshl_add_u64 v[4:5], v[4:5], 0, s[6:7]
	s_add_i32 m0, s21, 0x1a000
	s_add_i32 s77, s21, 0x8000
	s_add_i32 s78, s21, 0xa000
	global_load_lds_dwordx4 v[4:5], off
	v_lshl_add_u64 v[0:1], v[0:1], 0, s[6:7]
	s_mov_b32 m0, s77
	s_add_u32 s8, s26, 0x10080
	global_load_lds_dwordx4 v[0:1], off
	v_lshl_add_u64 v[0:1], v[2:3], 0, s[6:7]
	s_mov_b32 m0, s78
	s_addc_u32 s9, s27, 0
	global_load_lds_dwordx4 v[0:1], off
	s_add_i32 m0, s21, 0x1c000
	v_lshl_add_u64 v[0:1], s[8:9], 0, v[130:131]
	global_load_lds_dwordx4 v[0:1], off
	v_lshl_add_u64 v[0:1], s[8:9], 0, v[134:135]
	s_add_i32 m0, s21, 0x1e000
	s_sext_i32_i8 s87, s0
	global_load_lds_dwordx4 v[0:1], off
	s_waitcnt vmcnt(8)
	s_barrier
	v_and_b32_e32 v0, 15, v8
	v_ashrrev_i32_e32 v1, 6, v8
	v_and_b32_e32 v2, 48, v8
	v_readlane_b32 s0, v254, 3
	v_lshl_or_b32 v0, v0, 6, v2
	v_lshlrev_b32_e32 v3, 2, v8
	v_lshl_add_u32 v2, v1, 10, s0
	v_readlane_b32 s0, v254, 5
	v_and_b32_e32 v3, 32, v3
	s_waitcnt vmcnt(6)
	s_cmpk_lt_u32 s3, 0x100
	v_add_lshl_u32 v1, v1, s0, 10
	v_bitop3_b32 v2, v0, v2, v3 bitop3:0xde
	v_bitop3_b32 v140, v0, v1, v3 bitop3:0xde
	s_cselect_b64 s[8:9], -1, 0
	s_lshl_b32 s0, s33, 4
	s_add_i32 s81, 0, 0x10000
	s_add_i32 s82, 0, 0x14000
	s_and_b32 s79, s0, 0x3fffffc0
	s_ashr_i32 s80, s56, 31
	v_mov_b64_e32 v[136:137], 0x200
	v_mov_b64_e32 v[138:139], 0x1ff
	v_add_u32_e32 v141, s81, v140
	v_add_u32_e32 v142, s82, v140
	v_add_u32_e32 v143, 0, v2
	s_mov_b64 s[10:11], 0x40000
	s_mov_b32 s83, 0x40000
	s_mov_b64 s[12:13], 0x48000
	s_mov_b32 s84, 0x48000
	s_mov_b64 s[16:17], 0x50000
	s_mov_b32 s85, 0x50000
	s_mov_b64 s[18:19], 0x58000
	s_mov_b32 s86, 0x58000
	s_barrier
	s_branch .LBB0_1322

; #define PG8_STAGE(bufoff, gbase, voff) do { _Pragma("unroll") for (int _i = 0; _i < 2; ++_i) \
;         __builtin_amdgcn_global_load_lds((const unsigned*)((const char*)(gbase) + (voff)[_i]), (LAS unsigned*)(lds + (bufoff) + ldsw + _i * 8192), 16, 0, 0); } while (0)
; #define PG8_WAIT_V(n) asm volatile("s_waitcnt vmcnt(" #n ")" ::: "memory")
; #define PG8_BAR __builtin_amdgcn_s_barrier()
; template <class Epi>
; __device__ __forceinline__ void gemm_phase(LAS unsigned char* lds, const Gemm g, const StaticOrder& S, const Epi& E, const int wid) {
;     ...
;     for (int i = 0; i < 2; ++i) { int R, C; stage_rc(tid * 16 + i * 8192, R, C); const int Rb = Epi::PERM ? ((R & ~31) + perm32(R & 31)) : R;
;         voffA[i] = (unsigned)(R * lda + C) * 2u; voffB[i] = (unsigned)(Rb * K + C) * 2u; }
;     const size_t kstep = (size_t)(BK * 2);
;     const size_t hsA = (size_t)HALF * lda * 2, hsB = (size_t)HALF * K * 2;
;     const size_t tsA = 2 * hsA, tsB = 2 * hsB;
;     const unsigned ldsw = (unsigned)wid * 1024u;
;     const int aoff = lds_byte(wr * 64 + fr, fq * 8), boff = lds_byte(wc * 32 + fr, fq * 8);
;     ...
;     PG8_STAGE(PG8_SB(0, 0), cB, voffB); PG8_STAGE(PG8_SB(0, 1), cB + hsB, voffB); PG8_STAGE(PG8_SA(0, 0), cA, voffA); PG8_STAGE(PG8_SA(0, 1), cA + hsA, voffA);
;     if (wr == 1) PG8_BAR;
;     PG8_WAIT_V(2); PG8_BAR;
;     PG8_STAGE(PG8_SB(1, 0), cB + kstep, voffB); PG8_STAGE(PG8_SA(1, 0), cA + kstep, voffA); PG8_STAGE(PG8_SB(1, 1), cB + hsB + kstep, voffB);
;     PG8_WAIT_V(6); PG8_BAR;
.LBB0_1343:
	s_mov_b64 s[6:7], 0x80
	s_add_i32 m0, s29, 0x18000
	v_lshl_add_u64 v[6:7], v[6:7], 0, s[6:7]
	global_load_lds_dwordx4 v[6:7], off
	v_lshl_add_u64 v[4:5], v[4:5], 0, s[6:7]
	s_add_i32 m0, s29, 0x1a000
	s_add_i32 s55, s29, 0x8000
	s_add_i32 s57, s29, 0xa000
	global_load_lds_dwordx4 v[4:5], off
	v_lshl_add_u64 v[0:1], v[0:1], 0, s[6:7]
	s_mov_b32 m0, s55
	s_add_u32 s8, s30, 0x40080
	global_load_lds_dwordx4 v[0:1], off
	v_lshl_add_u64 v[0:1], v[2:3], 0, s[6:7]
	s_mov_b32 m0, s57
	s_addc_u32 s9, s31, 0
	global_load_lds_dwordx4 v[0:1], off
	s_add_i32 m0, s29, 0x1c000
	v_lshl_add_u64 v[0:1], s[8:9], 0, v[146:147]
	global_load_lds_dwordx4 v[0:1], off
	v_lshl_add_u64 v[0:1], s[8:9], 0, v[150:151]
	s_add_i32 m0, s29, 0x1e000
	s_sext_i32_i8 s60, s0
	global_load_lds_dwordx4 v[0:1], off
	s_waitcnt vmcnt(8)
	s_barrier
	v_and_b32_e32 v0, 15, v8
	v_ashrrev_i32_e32 v1, 6, v8
	v_and_b32_e32 v2, 48, v8
	v_readlane_b32 s0, v254, 3
	v_lshl_or_b32 v0, v0, 6, v2
	v_lshlrev_b32_e32 v3, 2, v8
	v_lshl_add_u32 v2, v1, 10, s0
	v_readlane_b32 s0, v254, 5
	v_and_b32_e32 v3, 32, v3
	v_bitop3_b32 v2, v0, v2, v3 bitop3:0xde
	v_add_lshl_u32 v1, v1, s0, 10
	v_bitop3_b32 v168, v0, v1, v3 bitop3:0xde
	v_lshlrev_b32_e32 v0, 14, v12
	v_and_b32_e32 v0, 0xffff8000, v0
	v_lshl_add_u32 v0, v13, 11, v0
	v_and_b32_e32 v1, 1, v12
	v_lshl_or_b32 v0, v1, 6, v0
	v_lshl_add_u32 v152, v14, 1, v0
	v_lshlrev_b32_e32 v0, 14, v9
	v_and_b32_e32 v0, 0xffff8000, v0
	s_waitcnt vmcnt(6)
	s_cmpk_lt_u32 s3, 0x100
	v_lshl_add_u32 v0, v10, 11, v0
	v_and_b32_e32 v1, 1, v9
	s_cselect_b64 s[8:9], -1, 0
	s_lshl_b32 s0, s33, 4
	v_lshl_or_b32 v0, v1, 6, v0
	s_add_i32 s58, 0, 0x10000
	s_add_i32 s59, 0, 0x14000
	s_and_b32 s3, s0, 0x3fffffc0
	s_ashr_i32 s33, s56, 31
	v_mov_b32_e32 v153, v147
	v_lshl_add_u32 v154, v11, 1, v0
	v_mov_b32_e32 v155, v147
	v_mov_b64_e32 v[156:157], 0x200
	v_mov_b64_e32 v[158:159], 0x1ff
	s_mov_b64 s[10:11], 0x100
	v_add_u32_e32 v169, s58, v168
	v_add_u32_e32 v170, s59, v168
	v_add_u32_e32 v171, 0, v2
	v_mov_b32_e32 v172, 0x358637bd
	s_mov_b64 s[12:13], 0x24000
	s_mov_b64 s[14:15], 0x20000
	s_mov_b64 s[16:17], 0x2c000
	s_mov_b64 s[18:19], 0x28000
	s_barrier
	s_branch .LBB0_1346
